# attention loop: first K-fragment LDS reads of each half issued before that half's DMA instructions
# speedup vs baseline: 1.0181x; 1.0049x over previous
.LBB0_433:
	ds_read_b128 v[64:67], v166 offset:49152
	ds_read_b128 v[68:71], v166 offset:57344
	ds_read_b128 v[176:179], v167 offset:49152
	ds_read_b128 v[198:201], v167 offset:57344
	ds_read_b128 v[202:205], v168 offset:49152
	ds_read_b128 v[210:213], v168 offset:57344
	s_add_u32 m0, s86, 0x8000
	s_nop 0
	global_load_lds_dwordx4 v247, s[82:83]
	s_add_u32 m0, s86, 0x8400
	s_nop 0
	global_load_lds_dwordx4 v248, s[82:83]
	s_add_u32 s82, s82, 0x8000
	s_addc_u32 s83, s83, 0
	v_exp_f32_e32 v142, v142
	v_exp_f32_e32 v143, v143
	s_waitcnt lgkmcnt(5)
	v_mfma_f32_32x32x16_bf16 v[80:95], v[64:67], v[124:127], 0
	v_exp_f32_e32 v180, v140
	v_exp_f32_e32 v181, v141
	v_exp_f32_e32 v206, v138
	v_exp_f32_e32 v207, v135
	v_exp_f32_e32 v148, v148
	v_exp_f32_e32 v149, v149
	v_exp_f32_e32 v209, v146
	s_waitcnt lgkmcnt(4)
	v_mfma_f32_32x32x16_bf16 v[64:79], v[68:71], v[124:127], 0
	v_cvt_pk_bf16_f32 v135, v192, v193
	v_cvt_pk_bf16_f32 v138, v182, v183
	v_cvt_pk_bf16_f32 v140, v185, v187
	v_cvt_pk_bf16_f32 v141, v188, v189
	s_nop 0
	s_waitcnt lgkmcnt(3)
	v_mfma_f32_32x32x16_bf16 v[80:95], v[176:179], v[120:123], v[80:95]
	ds_read_b128 v[176:179], v169 offset:49152
	ds_read_b128 v[214:217], v169 offset:57344
	ds_read_b128 v[218:221], v170 offset:49152
	ds_read_b128 v[222:225], v170 offset:57344
	ds_read_b128 v[226:229], v171 offset:49152
	ds_read_b128 v[230:233], v171 offset:57344
	ds_read_b128 v[234:237], v172 offset:49152
	ds_read_b128 v[238:241], v172 offset:57344
	s_waitcnt lgkmcnt(10)
	v_mfma_f32_32x32x16_bf16 v[64:79], v[198:201], v[120:123], v[64:79]
	ds_read_b128 v[198:201], v173 offset:49152
	ds_read_b128 v[242:245], v173 offset:57344
	s_waitcnt lgkmcnt(11)
	v_mfma_f32_32x32x16_bf16 v[80:95], v[202:205], v[112:115], v[80:95]
	v_exp_f32_e32 v205, v134
	v_add_f32_e32 v134, v191, v190
	v_add_f32_e32 v134, v192, v134
	v_add_f32_e32 v134, v193, v134
	v_add_f32_e32 v134, v194, v134
	v_add_f32_e32 v134, v196, v134
	s_waitcnt lgkmcnt(10)
	v_mfma_f32_32x32x16_bf16 v[64:79], v[210:213], v[112:115], v[64:79]
	v_add_f32_e32 v134, v195, v134
	v_add_f32_e32 v134, v197, v134
	v_add_f32_e32 v134, v182, v134
	v_add_f32_e32 v134, v183, v134
	v_add_f32_e32 v134, v184, v134
	v_add_f32_e32 v134, v186, v134
	v_add_f32_e32 v134, v185, v134
	s_waitcnt lgkmcnt(9)
	v_mfma_f32_32x32x16_bf16 v[80:95], v[176:179], v[116:119], v[80:95]
	v_add_f32_e32 v134, v187, v134
	v_add_f32_e32 v134, v188, v134
	v_add_f32_e32 v134, v189, v134
	v_add_f32_e32 v134, v142, v134
	v_exp_f32_e32 v202, v139
	v_add_f32_e32 v134, v143, v134
	v_exp_f32_e32 v203, v136
	s_waitcnt lgkmcnt(8)
	v_mfma_f32_32x32x16_bf16 v[64:79], v[214:217], v[116:119], v[64:79]
	v_add_f32_e32 v134, v180, v134
	v_exp_f32_e32 v204, v137
	v_add_f32_e32 v134, v181, v134
	v_add_f32_e32 v134, v206, v134
	v_add_f32_e32 v134, v202, v134
	v_add_f32_e32 v134, v203, v134
	v_add_f32_e32 v134, v204, v134
	s_waitcnt lgkmcnt(7)
	v_mfma_f32_32x32x16_bf16 v[80:95], v[218:221], v[108:111], v[80:95]
	v_add_f32_e32 v134, v205, v134
	v_exp_f32_e32 v210, v147
	v_add_f32_e32 v134, v207, v134
	v_exp_f32_e32 v211, v144
	v_add_f32_e32 v134, v148, v134
	v_exp_f32_e32 v212, v145
	v_add_f32_e32 v134, v149, v134
	s_waitcnt lgkmcnt(6)
	v_mfma_f32_32x32x16_bf16 v[64:79], v[222:225], v[108:111], v[64:79]
	v_add_f32_e32 v134, v209, v134
	v_add_f32_e32 v134, v210, v134
	v_add_f32_e32 v134, v211, v134
	v_add_f32_e32 v176, v212, v134
	v_cvt_pk_bf16_f32 v134, v190, v191
	v_cvt_pk_bf16_f32 v136, v194, v196
	s_waitcnt lgkmcnt(5)
	v_mfma_f32_32x32x16_bf16 v[80:95], v[226:229], v[104:107], v[80:95]
	v_cvt_pk_bf16_f32 v137, v195, v197
	v_cvt_pk_bf16_f32 v139, v184, v186
	v_cvt_pk_bf16_f32 v142, v142, v143
	s_waitcnt lgkmcnt(4)
	v_mfma_f32_32x32x16_bf16 v[64:79], v[230:233], v[104:107], v[64:79]
	v_cvt_pk_bf16_f32 v143, v180, v181
	v_cvt_pk_bf16_f32 v144, v206, v202
	v_cvt_pk_bf16_f32 v145, v203, v204
	v_cvt_pk_bf16_f32 v146, v205, v207
	v_cvt_pk_bf16_f32 v147, v148, v149
	v_cvt_pk_bf16_f32 v148, v209, v210
	v_cvt_pk_bf16_f32 v149, v211, v212
	s_waitcnt lgkmcnt(3)
	v_mfma_f32_32x32x16_bf16 v[80:95], v[234:237], v[100:103], v[80:95]
	s_waitcnt lgkmcnt(2)
	v_mfma_f32_32x32x16_bf16 v[64:79], v[238:241], v[100:103], v[64:79]
	s_waitcnt lgkmcnt(1)
	v_mfma_f32_32x32x16_bf16 v[80:95], v[198:201], v[96:99], v[80:95]
	s_waitcnt lgkmcnt(0)
	v_mfma_f32_32x32x16_bf16 v[64:79], v[242:245], v[96:99], v[64:79]
	ds_read_b64_tr_b16 v[196:197], v161 offset:0
	ds_read_b64_tr_b16 v[198:199], v161 offset:0x800
	ds_read_b64_tr_b16 v[200:201], v161 offset:0x1000
	ds_read_b64_tr_b16 v[202:203], v161 offset:0x1800
	ds_read_b64_tr_b16 v[204:205], v161 offset:0x2000
	ds_read_b64_tr_b16 v[206:207], v161 offset:0x2800
	ds_read_b64_tr_b16 v[210:211], v161 offset:0x3000
	ds_read_b64_tr_b16 v[212:213], v161 offset:0x3800
	s_waitcnt lgkmcnt(0)
	s_nop 0
	v_mfma_f32_32x32x16_bf16 v[0:15], v[134:137], v[196:199], v[0:15]
	ds_read_b64_tr_b16 v[196:197], v161 offset:0x200
	ds_read_b64_tr_b16 v[198:199], v161 offset:0xa00
	v_max_f32_e32 v234, v80, v81
	v_max3_f32 v234, v234, v82, v83
	v_max3_f32 v234, v234, v84, v85
	v_max3_f32 v234, v234, v86, v87
	v_max3_f32 v234, v234, v88, v89
	v_mfma_f32_32x32x16_bf16 v[0:15], v[138:141], v[200:203], v[0:15]
	ds_read_b64_tr_b16 v[200:201], v161 offset:0x1200
	ds_read_b64_tr_b16 v[202:203], v161 offset:0x1a00
	v_max3_f32 v234, v234, v90, v91
	v_max3_f32 v234, v234, v92, v93
	v_max3_f32 v234, v234, v94, v95
	v_max3_f32 v234, v234, v64, v65
	v_max3_f32 v234, v234, v66, v67
	v_mfma_f32_32x32x16_bf16 v[0:15], v[142:145], v[204:207], v[0:15]
	ds_read_b64_tr_b16 v[204:205], v161 offset:0x2200
	ds_read_b64_tr_b16 v[206:207], v161 offset:0x2a00
	ds_read_b64_tr_b16 v[214:215], v161 offset:0x3200
	ds_read_b64_tr_b16 v[216:217], v161 offset:0x3a00
	v_max3_f32 v234, v234, v68, v69
	v_max3_f32 v234, v234, v70, v71
	v_max3_f32 v234, v234, v72, v73
	v_max3_f32 v234, v234, v74, v75
	v_max3_f32 v234, v234, v76, v77
	s_waitcnt lgkmcnt(0)
	v_mfma_f32_32x32x16_bf16 v[0:15], v[146:149], v[210:213], v[0:15]
	v_max3_f32 v234, v234, v78, v79
	v_mov_b32_e32 v235, v234
	v_mfma_f32_32x32x16_bf16 v[48:63], v[134:137], v[196:199], v[48:63]
	ds_read_b64_tr_b16 v[196:197], v161 offset:0x400
	ds_read_b64_tr_b16 v[198:199], v161 offset:0xc00
	v_permlane32_swap_b32_e32 v234, v235
	v_max_f32_e32 v234, v234, v235
	v_mfma_f32_32x32x16_bf16 v[48:63], v[138:141], v[200:203], v[48:63]
	ds_read_b64_tr_b16 v[200:201], v161 offset:0x1400
	ds_read_b64_tr_b16 v[202:203], v161 offset:0x1c00
	v_sub_f32_e32 v235, v234, v175
	v_max_f32_e32 v234, v175, v234
	v_sub_f32_e32 v236, v175, v234
	v_mul_f32_e32 v236, 0x3e0293ee, v236
	v_mfma_f32_32x32x16_bf16 v[48:63], v[142:145], v[204:207], v[48:63]
	ds_read_b64_tr_b16 v[204:205], v161 offset:0x2400
	ds_read_b64_tr_b16 v[206:207], v161 offset:0x2c00
	ds_read_b64_tr_b16 v[210:211], v161 offset:0x3400
	ds_read_b64_tr_b16 v[212:213], v161 offset:0x3c00
	v_exp_f32_e32 v236, v236
	v_cmp_ge_f32_e32 vcc, s15, v235
	s_cmp_eq_u64 vcc, exec
	s_cselect_b64 s[8:9], -1, 0
	s_waitcnt lgkmcnt(0)
	v_mfma_f32_32x32x16_bf16 v[48:63], v[146:149], v[214:217], v[48:63]
	v_cndmask_b32_e64 v179, v236, 1.0, s[8:9]
	v_cndmask_b32_e64 v234, v234, v175, s[8:9]
	v_mul_f32_e32 v238, 0xbe0293ee, v234
	v_fmamk_f32 v88, v88, 0x3e0293ee, v238
	v_fmamk_f32 v89, v89, 0x3e0293ee, v238
	v_fmamk_f32 v80, v80, 0x3e0293ee, v238
	v_fmamk_f32 v81, v81, 0x3e0293ee, v238
	v_mfma_f32_32x32x16_bf16 v[32:47], v[134:137], v[196:199], v[32:47]
	ds_read_b64_tr_b16 v[196:197], v161 offset:0x600
	ds_read_b64_tr_b16 v[198:199], v161 offset:0xe00
	v_fmamk_f32 v82, v82, 0x3e0293ee, v238
	v_fmamk_f32 v83, v83, 0x3e0293ee, v238
	v_fmamk_f32 v84, v84, 0x3e0293ee, v238
	v_fmamk_f32 v85, v85, 0x3e0293ee, v238
	v_fmamk_f32 v86, v86, 0x3e0293ee, v238
	v_fmamk_f32 v87, v87, 0x3e0293ee, v238
	v_fmamk_f32 v90, v90, 0x3e0293ee, v238
	v_fmamk_f32 v91, v91, 0x3e0293ee, v238
	v_mfma_f32_32x32x16_bf16 v[32:47], v[138:141], v[200:203], v[32:47]
	ds_read_b64_tr_b16 v[200:201], v161 offset:0x1600
	ds_read_b64_tr_b16 v[202:203], v161 offset:0x1e00
	v_fmamk_f32 v92, v92, 0x3e0293ee, v238
	v_fmamk_f32 v93, v93, 0x3e0293ee, v238
	v_fmamk_f32 v94, v94, 0x3e0293ee, v238
	v_fmamk_f32 v95, v95, 0x3e0293ee, v238
	v_fmamk_f32 v188, v64, 0x3e0293ee, v238
	v_fmamk_f32 v189, v65, 0x3e0293ee, v238
	v_fmamk_f32 v190, v66, 0x3e0293ee, v238
	v_fmamk_f32 v191, v67, 0x3e0293ee, v238
	v_mfma_f32_32x32x16_bf16 v[32:47], v[142:145], v[204:207], v[32:47]
	ds_read_b64_tr_b16 v[204:205], v161 offset:0x2600
	ds_read_b64_tr_b16 v[206:207], v161 offset:0x2e00
	ds_read_b64_tr_b16 v[214:215], v161 offset:0x3600
	ds_read_b64_tr_b16 v[216:217], v161 offset:0x3e00
	v_fmamk_f32 v182, v70, 0x3e0293ee, v238
	v_fmamk_f32 v183, v71, 0x3e0293ee, v238
	v_fmamk_f32 v184, v72, 0x3e0293ee, v238
	v_fmamk_f32 v185, v73, 0x3e0293ee, v238
	v_fmamk_f32 v186, v74, 0x3e0293ee, v238
	v_fmamk_f32 v187, v75, 0x3e0293ee, v238
	s_waitcnt lgkmcnt(0)
	v_mfma_f32_32x32x16_bf16 v[32:47], v[146:149], v[210:213], v[32:47]
	v_fmamk_f32 v192, v68, 0x3e0293ee, v238
	v_fmamk_f32 v181, v69, 0x3e0293ee, v238
	v_fmamk_f32 v180, v76, 0x3e0293ee, v238
	v_mfma_f32_32x32x16_bf16 v[16:31], v[134:137], v[196:199], v[16:31]
	v_fmamk_f32 v193, v77, 0x3e0293ee, v238
	v_fmamk_f32 v194, v78, 0x3e0293ee, v238
	v_fmamk_f32 v177, v79, 0x3e0293ee, v238
	v_mov_b32_e32 v134, v234
	v_exp_f32_e32 v135, v88
	v_exp_f32_e32 v136, v89
	v_exp_f32_e32 v137, v90
	v_mfma_f32_32x32x16_bf16 v[16:31], v[138:141], v[200:203], v[16:31]
	v_exp_f32_e32 v139, v91
	v_exp_f32_e32 v138, v92
	v_exp_f32_e32 v140, v93
	v_exp_f32_e32 v141, v94
	v_mfma_f32_32x32x16_bf16 v[16:31], v[142:145], v[204:207], v[16:31]
	v_exp_f32_e32 v142, v95
	v_exp_f32_e32 v143, v80
	v_exp_f32_e32 v144, v81
	v_exp_f32_e32 v145, v82
	v_mfma_f32_32x32x16_bf16 v[16:31], v[146:149], v[214:217], v[16:31]
	v_exp_f32_e32 v146, v83
	v_exp_f32_e32 v147, v84
	v_exp_f32_e32 v149, v85
	v_exp_f32_e32 v148, v86
	v_exp_f32_e32 v175, v87
	v_cmp_gt_f32_e32 vcc, 1.0, v179
	s_waitcnt vmcnt(0)
	s_barrier
	s_cbranch_vccz .LBB0_437
	s_and_saveexec_b64 s[2:3], s[6:7]
	ds_write_b32 v158, v179 offset:128
	s_or_b64 exec, exec, s[2:3]
	s_waitcnt lgkmcnt(0)
	v_add_u32_e32 v234, v131, v128
	ds_read_b128 v[218:221], v234 offset:224
	ds_read_b128 v[222:225], v234 offset:192
	ds_read_b128 v[226:229], v234 offset:160
	ds_read_b128 v[230:233], v234 offset:128
	s_waitcnt lgkmcnt(3)
	v_pk_mul_f32 v[12:13], v[12:13], v[218:219]
	s_waitcnt lgkmcnt(2)
	v_pk_mul_f32 v[8:9], v[8:9], v[222:223]
	s_waitcnt lgkmcnt(1)
	v_pk_mul_f32 v[4:5], v[4:5], v[226:227]
	v_pk_mul_f32 v[14:15], v[14:15], v[220:221]
	v_pk_mul_f32 v[10:11], v[10:11], v[224:225]
	v_pk_mul_f32 v[6:7], v[6:7], v[228:229]
	s_waitcnt lgkmcnt(0)
	v_pk_mul_f32 v[2:3], v[2:3], v[232:233]
	v_pk_mul_f32 v[0:1], v[0:1], v[230:231]
	v_pk_mul_f32 v[60:61], v[60:61], v[218:219]
	v_pk_mul_f32 v[56:57], v[56:57], v[222:223]
	v_pk_mul_f32 v[52:53], v[52:53], v[226:227]
	v_pk_mul_f32 v[62:63], v[62:63], v[220:221]
	v_pk_mul_f32 v[58:59], v[58:59], v[224:225]
	v_pk_mul_f32 v[54:55], v[54:55], v[228:229]
	v_pk_mul_f32 v[50:51], v[50:51], v[232:233]
	v_pk_mul_f32 v[48:49], v[48:49], v[230:231]
	v_pk_mul_f32 v[44:45], v[44:45], v[218:219]
	v_pk_mul_f32 v[40:41], v[40:41], v[222:223]
	v_pk_mul_f32 v[36:37], v[36:37], v[226:227]
	v_pk_mul_f32 v[46:47], v[46:47], v[220:221]
	v_pk_mul_f32 v[42:43], v[42:43], v[224:225]
	v_pk_mul_f32 v[38:39], v[38:39], v[228:229]
	v_pk_mul_f32 v[34:35], v[34:35], v[232:233]
	v_pk_mul_f32 v[32:33], v[32:33], v[230:231]
	v_pk_mul_f32 v[28:29], v[28:29], v[218:219]
	v_pk_mul_f32 v[24:25], v[24:25], v[222:223]
	v_pk_mul_f32 v[20:21], v[20:21], v[226:227]
	v_pk_mul_f32 v[30:31], v[30:31], v[220:221]
	v_pk_mul_f32 v[26:27], v[26:27], v[224:225]
	v_pk_mul_f32 v[22:23], v[22:23], v[228:229]
	v_pk_mul_f32 v[18:19], v[18:19], v[232:233]
	v_pk_mul_f32 v[16:17], v[16:17], v[230:231]
.LBB0_437:
	ds_read_b128 v[64:67], v166 offset:32768
	ds_read_b128 v[68:71], v166 offset:40960
	ds_read_b128 v[196:199], v167 offset:32768
	ds_read_b128 v[200:203], v167 offset:40960
	ds_read_b128 v[204:207], v168 offset:32768
	ds_read_b128 v[210:213], v168 offset:40960
	s_add_u32 m0, s86, 0x0
	s_nop 0
	global_load_lds_dwordx4 v249, s[84:85]
	s_add_u32 m0, s86, 0x380
	s_nop 0
	global_load_lds_dwordx4 v249, s[84:85] offset:128
	s_add_u32 s84, s84, 0x8000
	s_addc_u32 s85, s85, 0
	s_add_u32 m0, s86, 0xc000
	s_nop 0
	global_load_lds_dwordx4 v247, s[82:83]
	s_add_u32 m0, s86, 0xc400
	s_nop 0
	global_load_lds_dwordx4 v248, s[82:83]
	s_add_u32 s82, s82, 0x8000
	s_addc_u32 s83, s83, 0
	v_exp_f32_e32 v188, v188
	v_exp_f32_e32 v189, v189
	s_waitcnt lgkmcnt(5)
	v_mfma_f32_32x32x16_bf16 v[80:95], v[64:67], v[124:127], 0
	v_exp_f32_e32 v190, v190
	v_exp_f32_e32 v191, v191
	v_exp_f32_e32 v192, v192
	v_exp_f32_e32 v195, v181
	v_exp_f32_e32 v182, v182
	v_exp_f32_e32 v183, v183
	v_exp_f32_e32 v184, v184
	s_waitcnt lgkmcnt(4)
	v_mfma_f32_32x32x16_bf16 v[64:79], v[68:71], v[124:127], 0
	v_exp_f32_e32 v185, v185
	v_exp_f32_e32 v186, v186
	v_exp_f32_e32 v187, v187
	v_exp_f32_e32 v193, v193
	v_exp_f32_e32 v194, v194
	v_exp_f32_e32 v177, v177
	s_waitcnt lgkmcnt(3)
	v_mfma_f32_32x32x16_bf16 v[80:95], v[196:199], v[120:123], v[80:95]
	ds_read_b128 v[196:199], v169 offset:32768
	ds_read_b128 v[214:217], v169 offset:40960
	ds_read_b128 v[218:221], v170 offset:32768
	ds_read_b128 v[222:225], v170 offset:40960
	ds_read_b128 v[226:229], v171 offset:32768
	ds_read_b128 v[230:233], v171 offset:40960
	ds_read_b128 v[234:237], v172 offset:32768
	ds_read_b128 v[238:241], v172 offset:40960
	s_waitcnt lgkmcnt(10)
	v_mfma_f32_32x32x16_bf16 v[64:79], v[200:203], v[120:123], v[64:79]
	ds_read_b128 v[200:203], v173 offset:32768
	ds_read_b128 v[242:245], v173 offset:40960
	s_waitcnt lgkmcnt(11)
	v_mfma_f32_32x32x16_bf16 v[80:95], v[204:207], v[112:115], v[80:95]
	v_exp_f32_e32 v204, v180
	v_add_f32_e32 v180, v144, v143
	v_add_f32_e32 v180, v145, v180
	v_add_f32_e32 v180, v146, v180
	v_add_f32_e32 v180, v147, v180
	v_add_f32_e32 v180, v149, v180
	s_waitcnt lgkmcnt(10)
	v_mfma_f32_32x32x16_bf16 v[64:79], v[210:213], v[112:115], v[64:79]
	v_add_f32_e32 v180, v148, v180
	v_add_f32_e32 v180, v175, v180
	v_add_f32_e32 v180, v135, v180
	v_add_f32_e32 v180, v136, v180
	v_add_f32_e32 v180, v137, v180
	v_add_f32_e32 v180, v139, v180
	v_add_f32_e32 v180, v138, v180
	s_waitcnt lgkmcnt(9)
	v_mfma_f32_32x32x16_bf16 v[80:95], v[196:199], v[116:119], v[80:95]
	v_add_f32_e32 v180, v140, v180
	v_add_f32_e32 v180, v141, v180
	v_add_f32_e32 v180, v142, v180
	v_add_f32_e32 v180, v188, v180
	v_add_f32_e32 v180, v189, v180
	v_add_f32_e32 v180, v190, v180
	v_add_f32_e32 v180, v191, v180
	s_waitcnt lgkmcnt(8)
	v_mfma_f32_32x32x16_bf16 v[64:79], v[214:217], v[116:119], v[64:79]
	v_add_f32_e32 v180, v192, v180
	v_add_f32_e32 v180, v195, v180
	v_add_f32_e32 v180, v182, v180
	v_add_f32_e32 v180, v183, v180
	v_add_f32_e32 v180, v184, v180
	v_add_f32_e32 v180, v185, v180
	v_add_f32_e32 v180, v186, v180
	s_waitcnt lgkmcnt(7)
	v_mfma_f32_32x32x16_bf16 v[80:95], v[218:221], v[108:111], v[80:95]
	v_add_f32_e32 v180, v187, v180
	v_add_f32_e32 v180, v204, v180
	v_add_f32_e32 v180, v193, v180
	v_add_f32_e32 v180, v194, v180
	v_add_f32_e32 v180, v177, v180
	s_waitcnt lgkmcnt(6)
	v_mfma_f32_32x32x16_bf16 v[64:79], v[222:225], v[108:111], v[64:79]
	v_cvt_pk_bf16_f32 v144, v143, v144
	v_cvt_pk_bf16_f32 v145, v145, v146
	v_cvt_pk_bf16_f32 v146, v147, v149
	v_cvt_pk_bf16_f32 v147, v148, v175
	v_cvt_pk_bf16_f32 v136, v135, v136
	v_cvt_pk_bf16_f32 v137, v137, v139
	v_cvt_pk_bf16_f32 v138, v138, v140
	s_waitcnt lgkmcnt(5)
	v_mfma_f32_32x32x16_bf16 v[80:95], v[226:229], v[104:107], v[80:95]
	v_cvt_pk_bf16_f32 v139, v141, v142
	v_cvt_pk_bf16_f32 v140, v188, v189
	v_cvt_pk_bf16_f32 v141, v190, v191
	v_cvt_pk_bf16_f32 v142, v192, v195
	v_cvt_pk_bf16_f32 v143, v182, v183
	v_cvt_pk_bf16_f32 v182, v184, v185
	v_cvt_pk_bf16_f32 v183, v186, v187
	s_waitcnt lgkmcnt(4)
	v_mfma_f32_32x32x16_bf16 v[64:79], v[230:233], v[104:107], v[64:79]
	v_cvt_pk_bf16_f32 v184, v204, v193
	v_cvt_pk_bf16_f32 v185, v194, v177
	s_waitcnt lgkmcnt(3)
	v_mfma_f32_32x32x16_bf16 v[80:95], v[234:237], v[100:103], v[80:95]
	s_waitcnt lgkmcnt(2)
	v_mfma_f32_32x32x16_bf16 v[64:79], v[238:241], v[100:103], v[64:79]
	s_waitcnt lgkmcnt(1)
	v_mfma_f32_32x32x16_bf16 v[80:95], v[200:203], v[96:99], v[80:95]
	s_waitcnt lgkmcnt(0)
	v_mfma_f32_32x32x16_bf16 v[64:79], v[242:245], v[96:99], v[64:79]
	ds_read_b64_tr_b16 v[202:203], v160 offset:0
	ds_read_b64_tr_b16 v[204:205], v160 offset:0x800
	ds_read_b64_tr_b16 v[210:211], v160 offset:0x1000
	ds_read_b64_tr_b16 v[212:213], v160 offset:0x1800
	ds_read_b64_tr_b16 v[214:215], v160 offset:0x2000
	ds_read_b64_tr_b16 v[216:217], v160 offset:0x2800
	ds_read_b64_tr_b16 v[218:219], v160 offset:0x3000
	ds_read_b64_tr_b16 v[220:221], v160 offset:0x3800
	s_waitcnt lgkmcnt(0)
	s_nop 0
	v_mfma_f32_32x32x16_bf16 v[0:15], v[144:147], v[202:205], v[0:15]
	ds_read_b64_tr_b16 v[202:203], v160 offset:0x200
	ds_read_b64_tr_b16 v[204:205], v160 offset:0xa00
	v_max_f32_e32 v242, v80, v81
	v_max3_f32 v242, v242, v82, v83
	v_max3_f32 v242, v242, v84, v85
	v_max3_f32 v242, v242, v86, v87
	v_max3_f32 v242, v242, v88, v89
	v_mfma_f32_32x32x16_bf16 v[0:15], v[136:139], v[210:213], v[0:15]
	ds_read_b64_tr_b16 v[210:211], v160 offset:0x1200
	ds_read_b64_tr_b16 v[212:213], v160 offset:0x1a00
	v_max3_f32 v242, v242, v90, v91
	v_max3_f32 v242, v242, v92, v93
	v_max3_f32 v242, v242, v94, v95
	v_max3_f32 v242, v242, v64, v65
	v_max3_f32 v242, v242, v66, v67
	v_mfma_f32_32x32x16_bf16 v[0:15], v[140:143], v[214:217], v[0:15]
	ds_read_b64_tr_b16 v[214:215], v160 offset:0x2200
	ds_read_b64_tr_b16 v[216:217], v160 offset:0x2a00
	ds_read_b64_tr_b16 v[222:223], v160 offset:0x3200
	ds_read_b64_tr_b16 v[224:225], v160 offset:0x3a00
	v_max3_f32 v242, v242, v68, v69
	v_max3_f32 v242, v242, v70, v71
	v_max3_f32 v242, v242, v72, v73
	v_max3_f32 v242, v242, v74, v75
	v_max3_f32 v242, v242, v76, v77
	s_waitcnt lgkmcnt(0)
	v_mfma_f32_32x32x16_bf16 v[0:15], v[182:185], v[218:221], v[0:15]
	v_max3_f32 v242, v242, v78, v79
	v_mov_b32_e32 v243, v242
	v_mfma_f32_32x32x16_bf16 v[48:63], v[144:147], v[202:205], v[48:63]
	ds_read_b64_tr_b16 v[202:203], v160 offset:0x400
	ds_read_b64_tr_b16 v[204:205], v160 offset:0xc00
	v_permlane32_swap_b32_e32 v242, v243
	v_max_f32_e32 v242, v242, v243
	v_mfma_f32_32x32x16_bf16 v[48:63], v[136:139], v[210:213], v[48:63]
	ds_read_b64_tr_b16 v[210:211], v160 offset:0x1400
	ds_read_b64_tr_b16 v[212:213], v160 offset:0x1c00
	v_sub_f32_e32 v243, v242, v134
	v_max_f32_e32 v242, v134, v242
	v_sub_f32_e32 v148, v134, v242
	v_mul_f32_e32 v148, 0x3e0293ee, v148
	v_mfma_f32_32x32x16_bf16 v[48:63], v[140:143], v[214:217], v[48:63]
	ds_read_b64_tr_b16 v[214:215], v160 offset:0x2400
	ds_read_b64_tr_b16 v[216:217], v160 offset:0x2c00
	ds_read_b64_tr_b16 v[218:219], v160 offset:0x3400
	ds_read_b64_tr_b16 v[220:221], v160 offset:0x3c00
	v_exp_f32_e32 v148, v148
	v_cmp_ge_f32_e32 vcc, s15, v243
	s_cmp_eq_u64 vcc, exec
	s_cselect_b64 s[8:9], -1, 0
	s_waitcnt lgkmcnt(0)
	v_mfma_f32_32x32x16_bf16 v[48:63], v[182:185], v[222:225], v[48:63]
	v_cndmask_b32_e64 v177, v148, 1.0, s[8:9]
	v_cndmask_b32_e64 v175, v242, v134, s[8:9]
	v_mul_f32_e32 v244, 0xbe0293ee, v175
	v_fmamk_f32 v80, v80, 0x3e0293ee, v244
	v_fmamk_f32 v81, v81, 0x3e0293ee, v244
	v_fmamk_f32 v82, v82, 0x3e0293ee, v244
	v_fmamk_f32 v83, v83, 0x3e0293ee, v244
	v_mfma_f32_32x32x16_bf16 v[32:47], v[144:147], v[202:205], v[32:47]
	ds_read_b64_tr_b16 v[202:203], v160 offset:0x600
	ds_read_b64_tr_b16 v[204:205], v160 offset:0xe00
	v_fmamk_f32 v84, v84, 0x3e0293ee, v244
	v_fmamk_f32 v85, v85, 0x3e0293ee, v244
	v_fmamk_f32 v86, v86, 0x3e0293ee, v244
	v_fmamk_f32 v87, v87, 0x3e0293ee, v244
	v_fmamk_f32 v88, v88, 0x3e0293ee, v244
	v_fmamk_f32 v89, v89, 0x3e0293ee, v244
	v_fmamk_f32 v90, v90, 0x3e0293ee, v244
	v_fmamk_f32 v91, v91, 0x3e0293ee, v244
	v_mfma_f32_32x32x16_bf16 v[32:47], v[136:139], v[210:213], v[32:47]
	ds_read_b64_tr_b16 v[210:211], v160 offset:0x1600
	ds_read_b64_tr_b16 v[212:213], v160 offset:0x1e00
	v_fmamk_f32 v92, v92, 0x3e0293ee, v244
	v_fmamk_f32 v93, v93, 0x3e0293ee, v244
	v_fmamk_f32 v94, v94, 0x3e0293ee, v244
	v_fmamk_f32 v95, v95, 0x3e0293ee, v244
	v_fmamk_f32 v134, v72, 0x3e0293ee, v244
	v_fmamk_f32 v135, v73, 0x3e0293ee, v244
	v_fmamk_f32 v148, v74, 0x3e0293ee, v244
	v_fmamk_f32 v149, v75, 0x3e0293ee, v244
	v_mfma_f32_32x32x16_bf16 v[32:47], v[140:143], v[214:217], v[32:47]
	ds_read_b64_tr_b16 v[214:215], v160 offset:0x2600
	ds_read_b64_tr_b16 v[216:217], v160 offset:0x2e00
	ds_read_b64_tr_b16 v[222:223], v160 offset:0x3600
	ds_read_b64_tr_b16 v[224:225], v160 offset:0x3e00
	v_exp_f32_e32 v190, v80
	v_exp_f32_e32 v191, v81
	v_exp_f32_e32 v192, v82
	s_waitcnt lgkmcnt(0)
	v_mfma_f32_32x32x16_bf16 v[32:47], v[182:185], v[218:221], v[32:47]
	v_exp_f32_e32 v193, v83
	v_exp_f32_e32 v194, v84
	v_exp_f32_e32 v196, v85
	v_mfma_f32_32x32x16_bf16 v[16:31], v[144:147], v[202:205], v[16:31]
	v_fmamk_f32 v144, v78, 0x3e0293ee, v244
	v_fmamk_f32 v145, v79, 0x3e0293ee, v244
	v_fmamk_f32 v146, v76, 0x3e0293ee, v244
	v_fmamk_f32 v147, v77, 0x3e0293ee, v244
	v_exp_f32_e32 v195, v86
	v_exp_f32_e32 v197, v87
	v_mfma_f32_32x32x16_bf16 v[16:31], v[136:139], v[210:213], v[16:31]
	v_fmamk_f32 v136, v70, 0x3e0293ee, v244
	v_fmamk_f32 v137, v71, 0x3e0293ee, v244
	v_fmamk_f32 v138, v68, 0x3e0293ee, v244
	v_fmamk_f32 v139, v69, 0x3e0293ee, v244
	v_exp_f32_e32 v186, v91
	v_exp_f32_e32 v187, v93
	v_mfma_f32_32x32x16_bf16 v[16:31], v[140:143], v[214:217], v[16:31]
	v_fmamk_f32 v140, v66, 0x3e0293ee, v244
	v_fmamk_f32 v141, v67, 0x3e0293ee, v244
	v_fmamk_f32 v142, v64, 0x3e0293ee, v244
	v_fmamk_f32 v143, v65, 0x3e0293ee, v244
	v_exp_f32_e32 v188, v94
	v_exp_f32_e32 v189, v95
	v_mfma_f32_32x32x16_bf16 v[16:31], v[182:185], v[222:225], v[16:31]
	v_exp_f32_e32 v182, v88
	v_exp_f32_e32 v183, v89
	v_exp_f32_e32 v184, v90
	v_exp_f32_e32 v185, v92
	v_cmp_gt_f32_e32 vcc, 1.0, v177
	s_waitcnt vmcnt(0)
	s_barrier
	s_add_u32 m0, s86, 0x4000
	s_nop 0
	global_load_lds_dwordx4 v249, s[84:85]
	s_add_u32 m0, s86, 0x4380
	s_nop 0
	global_load_lds_dwordx4 v249, s[84:85] offset:128
	s_add_u32 s84, s84, 0x8000
	s_addc_u32 s85, s85, 0
	s_cbranch_vccz .LBB0_441
	s_and_saveexec_b64 s[2:3], s[6:7]
	ds_write_b32 v158, v177 offset:128
	s_or_b64 exec, exec, s[2:3]
	s_waitcnt lgkmcnt(0)
	v_add_u32_e32 v242, v131, v128
	ds_read_b128 v[226:229], v242 offset:224
	ds_read_b128 v[230:233], v242 offset:192
	ds_read_b128 v[234:237], v242 offset:160
	ds_read_b128 v[238:241], v242 offset:128
	s_waitcnt lgkmcnt(3)
	v_pk_mul_f32 v[12:13], v[12:13], v[226:227]
	s_waitcnt lgkmcnt(2)
	v_pk_mul_f32 v[8:9], v[8:9], v[230:231]
	s_waitcnt lgkmcnt(1)
	v_pk_mul_f32 v[4:5], v[4:5], v[234:235]
	v_pk_mul_f32 v[14:15], v[14:15], v[228:229]
	v_pk_mul_f32 v[10:11], v[10:11], v[232:233]
	v_pk_mul_f32 v[6:7], v[6:7], v[236:237]
	s_waitcnt lgkmcnt(0)
	v_pk_mul_f32 v[2:3], v[2:3], v[240:241]
	v_pk_mul_f32 v[0:1], v[0:1], v[238:239]
	v_pk_mul_f32 v[60:61], v[60:61], v[226:227]
	v_pk_mul_f32 v[56:57], v[56:57], v[230:231]
	v_pk_mul_f32 v[52:53], v[52:53], v[234:235]
	v_pk_mul_f32 v[62:63], v[62:63], v[228:229]
	v_pk_mul_f32 v[58:59], v[58:59], v[232:233]
	v_pk_mul_f32 v[54:55], v[54:55], v[236:237]
	v_pk_mul_f32 v[50:51], v[50:51], v[240:241]
	v_pk_mul_f32 v[48:49], v[48:49], v[238:239]
	v_pk_mul_f32 v[44:45], v[44:45], v[226:227]
	v_pk_mul_f32 v[40:41], v[40:41], v[230:231]
	v_pk_mul_f32 v[36:37], v[36:37], v[234:235]
	v_pk_mul_f32 v[46:47], v[46:47], v[228:229]
	v_pk_mul_f32 v[42:43], v[42:43], v[232:233]
	v_pk_mul_f32 v[38:39], v[38:39], v[236:237]
	v_pk_mul_f32 v[34:35], v[34:35], v[240:241]
	v_pk_mul_f32 v[32:33], v[32:33], v[238:239]
	v_pk_mul_f32 v[28:29], v[28:29], v[226:227]
	v_pk_mul_f32 v[24:25], v[24:25], v[230:231]
	v_pk_mul_f32 v[20:21], v[20:21], v[234:235]
	v_pk_mul_f32 v[30:31], v[30:31], v[228:229]
	v_pk_mul_f32 v[26:27], v[26:27], v[232:233]
	v_pk_mul_f32 v[22:23], v[22:23], v[236:237]
	v_pk_mul_f32 v[18:19], v[18:19], v[240:241]
	v_pk_mul_f32 v[16:17], v[16:17], v[238:239]
